# in-proj K-loop: the static priority raise given to waves 0-3 instead of waves 4-7 (polarity A/B of the earlier static-priority change)
# speedup vs baseline: 1.0041x; 1.0020x over previous
;     __device__ __forceinline__ bool next(int i, Unit& u) const { if (i) return false; u.pm = pm; u.pn = pn; return true; }
;     __device__ __forceinline__ bool next(int i, Unit& u) const { if (i >= 5) return false; int t = i + rot; t = t >= 5 ? t - 5 : t; u.pm = pm; u.pn = e + 8 * t; return true; }
; template <class Epi, class Sched, bool ALIGN_EPI, bool SP2>
; __device__ __forceinline__ void gemm_phase(LAS unsigned char* lds, const Gemm g, const Sched& S, const Epi& E, int tid_in) {
;     ...
;     for (;;) {
;         const bool has_next = S.next(ui + 1, nxt);
;         const unsigned nA = has_next ? (unsigned)nxt.pm * tstepA : cA, nB = has_next ? (unsigned)nxt.pn * tstepB : cB;
;         for (int t = 0; t < nt; t += 2) {
.LBB0_136:
	v_readlane_b32 s2, v255, 30
	v_readlane_b32 s3, v255, 31
	s_nop 0
	s_and_b64 vcc, exec, s[2:3]
	s_cbranch_vccz .Lprio_skip
	s_setprio 1
